# prep phase: all 256 blocks share the 1264 short items (table blocks were idle after table deferral), on top of mod_item MLP
# speedup vs baseline: 1.0102x; 1.0002x over previous
.LBB0_1792:
	s_andn2_b64 vcc, exec, s[0:1]
	s_cbranch_vccnz .LBB0_1903
	s_cmpk_lg_i32 s89, 0x100
	s_cbranch_scc1 .Lal_orig
	v_readlane_b32 s2, v255, 61
	s_cmp_lg_u32 s2, 0
	s_cbranch_scc0 .Lal_items
.Lal_orig:
	v_readlane_b32 s2, v253, 11
	v_readlane_b32 s3, v253, 12
	s_mov_b64 s[0:1], -1
	s_and_b64 vcc, exec, s[2:3]
	s_cbranch_vccz .LBB0_1830
	v_readlane_b32 s0, v253, 13
	v_readlane_b32 s1, v253, 14
	s_andn2_b64 vcc, exec, s[0:1]
	s_cbranch_vccnz .LBB0_1829
.Lal_items:
	s_sub_i32 s40, s89, 32
	s_add_u32 s0, s72, 0x1c80000
	s_addc_u32 s1, s73, 0
	s_add_u32 s2, s72, 0x1180000
	s_addc_u32 s3, s73, 0
	s_add_u32 s4, s72, 0x2200000
	s_addc_u32 s5, s73, 0
	s_add_u32 s6, s72, 0xf80000
	s_addc_u32 s7, s73, 0
	s_add_u32 s41, s72, 0xc80000
	s_addc_u32 s42, s73, 0
	s_add_u32 s8, s72, 0x100000
	s_addc_u32 s9, s73, 0
	v_readlane_b32 s43, v253, 15
	s_cmpk_lg_i32 s89, 0x100
	s_cbranch_scc1 .Lal_k
	v_readlane_b32 s44, v255, 61
	s_cmp_lg_u32 s44, 0
	s_cbranch_scc1 .Lal_k
	v_readlane_b32 s43, v254, 42
	s_movk_i32 s40, 0x100
